# remaining accumulator zeroing done by eight 32x32 matrix instructions with zero operands
# speedup vs baseline: 1.0618x; 1.0002x over previous
.LBB0_202:
	s_andn2_b64 vcc, exec, s[50:51]
	s_cbranch_vccnz .Lcoldzero_1
	s_add_u32 s10, s6, 0x100
	s_addc_u32 s11, s7, 0
	s_add_u32 s6, s8, 0x80
	v_mov_b64_e32 v[224:225], 0
	v_mov_b64_e32 v[226:227], 0
	v_mov_b64_e32 v[228:229], 0
	v_mov_b64_e32 v[230:231], 0
	s_nop 1
	v_mfma_f32_32x32x16_bf16 v[0:15], v[224:227], v[228:231], 0
	v_mfma_f32_32x32x16_bf16 v[16:31], v[224:227], v[228:231], 0
	v_mfma_f32_32x32x16_bf16 v[32:47], v[224:227], v[228:231], 0
	v_mfma_f32_32x32x16_bf16 v[48:63], v[224:227], v[228:231], 0
	v_mfma_f32_32x32x16_bf16 v[64:79], v[224:227], v[228:231], 0
	v_mfma_f32_32x32x16_bf16 v[80:95], v[224:227], v[228:231], 0
	v_mfma_f32_32x32x16_bf16 v[96:111], v[224:227], v[228:231], 0
	v_mfma_f32_32x32x16_bf16 v[112:127], v[224:227], v[228:231], 0
	s_addc_u32 s7, s9, 0
	s_mov_b32 s8, 0

.LBB0_275:
	s_andn2_b64 vcc, exec, s[48:49]
	s_cbranch_vccnz .Lcoldzero_2
	s_add_u32 s10, s6, 0x100
	s_addc_u32 s11, s7, 0
	s_add_u32 s6, s8, 0x80
	v_mov_b64_e32 v[224:225], 0
	v_mov_b64_e32 v[226:227], 0
	v_mov_b64_e32 v[228:229], 0
	v_mov_b64_e32 v[230:231], 0
	s_nop 1
	v_mfma_f32_32x32x16_bf16 v[0:15], v[224:227], v[228:231], 0
	v_mfma_f32_32x32x16_bf16 v[16:31], v[224:227], v[228:231], 0
	v_mfma_f32_32x32x16_bf16 v[32:47], v[224:227], v[228:231], 0
	v_mfma_f32_32x32x16_bf16 v[48:63], v[224:227], v[228:231], 0
	v_mfma_f32_32x32x16_bf16 v[64:79], v[224:227], v[228:231], 0
	v_mfma_f32_32x32x16_bf16 v[80:95], v[224:227], v[228:231], 0
	v_mfma_f32_32x32x16_bf16 v[96:111], v[224:227], v[228:231], 0
	v_mfma_f32_32x32x16_bf16 v[112:127], v[224:227], v[228:231], 0
	s_addc_u32 s7, s9, 0
	s_mov_b32 s8, 0

.LBB0_403:
	s_andn2_b64 vcc, exec, s[40:41]
	s_cbranch_vccnz .Lcoldzero_3
	s_add_u32 s10, s6, 0x100
	s_addc_u32 s11, s7, 0
	s_add_u32 s6, s8, 0x80
	v_mov_b64_e32 v[224:225], 0
	v_mov_b64_e32 v[226:227], 0
	v_mov_b64_e32 v[228:229], 0
	v_mov_b64_e32 v[230:231], 0
	s_nop 1
	v_mfma_f32_32x32x16_bf16 v[0:15], v[224:227], v[228:231], 0
	v_mfma_f32_32x32x16_bf16 v[16:31], v[224:227], v[228:231], 0
	v_mfma_f32_32x32x16_bf16 v[32:47], v[224:227], v[228:231], 0
	v_mfma_f32_32x32x16_bf16 v[48:63], v[224:227], v[228:231], 0
	v_mfma_f32_32x32x16_bf16 v[64:79], v[224:227], v[228:231], 0
	v_mfma_f32_32x32x16_bf16 v[80:95], v[224:227], v[228:231], 0
	v_mfma_f32_32x32x16_bf16 v[96:111], v[224:227], v[228:231], 0
	v_mfma_f32_32x32x16_bf16 v[112:127], v[224:227], v[228:231], 0
	s_addc_u32 s7, s9, 0
	s_mov_b32 s8, 0

.LBB0_933:
	s_andn2_b64 vcc, exec, s[40:41]
	s_cbranch_vccnz .Lcoldzero_5
	s_add_u32 s10, s6, 0x100
	s_addc_u32 s11, s7, 0
	s_add_u32 s6, s8, 0x80
	v_mov_b64_e32 v[224:225], 0
	v_mov_b64_e32 v[226:227], 0
	v_mov_b64_e32 v[228:229], 0
	v_mov_b64_e32 v[230:231], 0
	s_nop 1
	v_mfma_f32_32x32x16_bf16 v[0:15], v[224:227], v[228:231], 0
	v_mfma_f32_32x32x16_bf16 v[16:31], v[224:227], v[228:231], 0
	v_mfma_f32_32x32x16_bf16 v[32:47], v[224:227], v[228:231], 0
	v_mfma_f32_32x32x16_bf16 v[48:63], v[224:227], v[228:231], 0
	v_mfma_f32_32x32x16_bf16 v[64:79], v[224:227], v[228:231], 0
	v_mfma_f32_32x32x16_bf16 v[96:111], v[224:227], v[228:231], 0
	v_mfma_f32_32x32x16_bf16 v[112:127], v[224:227], v[228:231], 0
	v_mov_b64_e32 v[84:85], 0
	v_mov_b64_e32 v[86:87], 0
	v_mov_b64_e32 v[88:89], 0
	v_mov_b64_e32 v[90:91], 0
	v_mov_b64_e32 v[92:93], 0
	v_mov_b64_e32 v[94:95], 0
	v_mov_b64_e32 v[128:129], 0
	v_mov_b64_e32 v[130:131], 0
	s_addc_u32 s7, s9, 0
	s_mov_b32 s8, 0

.LBB0_1057:
	s_andn2_b64 vcc, exec, s[46:47]
	s_cbranch_vccnz .Lcoldzero_6
	s_add_u32 s10, s6, 0x100
	s_addc_u32 s11, s7, 0
	s_add_u32 s6, s8, 0x80
	v_mov_b64_e32 v[224:225], 0
	v_mov_b64_e32 v[226:227], 0
	v_mov_b64_e32 v[228:229], 0
	v_mov_b64_e32 v[230:231], 0
	s_nop 1
	v_mfma_f32_32x32x16_bf16 v[0:15], v[224:227], v[228:231], 0
	v_mfma_f32_32x32x16_bf16 v[16:31], v[224:227], v[228:231], 0
	v_mfma_f32_32x32x16_bf16 v[32:47], v[224:227], v[228:231], 0
	v_mfma_f32_32x32x16_bf16 v[48:63], v[224:227], v[228:231], 0
	v_mfma_f32_32x32x16_bf16 v[64:79], v[224:227], v[228:231], 0
	v_mfma_f32_32x32x16_bf16 v[80:95], v[224:227], v[228:231], 0
	v_mfma_f32_32x32x16_bf16 v[96:111], v[224:227], v[228:231], 0
	v_mfma_f32_32x32x16_bf16 v[112:127], v[224:227], v[228:231], 0
	s_addc_u32 s7, s9, 0
	s_mov_b32 s8, 0

.LBB0_1130:
	s_andn2_b64 vcc, exec, s[4:5]
	s_cbranch_vccnz .Lcoldzero_7
	s_add_u32 s10, s6, 0x100
	s_addc_u32 s11, s7, 0
	s_add_u32 s6, s8, 0x80
	v_mov_b64_e32 v[224:225], 0
	v_mov_b64_e32 v[226:227], 0
	v_mov_b64_e32 v[228:229], 0
	v_mov_b64_e32 v[230:231], 0
	s_nop 1
	v_mfma_f32_32x32x16_bf16 v[0:15], v[224:227], v[228:231], 0
	v_mfma_f32_32x32x16_bf16 v[16:31], v[224:227], v[228:231], 0
	v_mfma_f32_32x32x16_bf16 v[32:47], v[224:227], v[228:231], 0
	v_mfma_f32_32x32x16_bf16 v[48:63], v[224:227], v[228:231], 0
	v_mfma_f32_32x32x16_bf16 v[64:79], v[224:227], v[228:231], 0
	v_mfma_f32_32x32x16_bf16 v[80:95], v[224:227], v[228:231], 0
	v_mfma_f32_32x32x16_bf16 v[96:111], v[224:227], v[228:231], 0
	v_mfma_f32_32x32x16_bf16 v[112:127], v[224:227], v[228:231], 0
	s_addc_u32 s7, s9, 0
	s_mov_b32 s8, 0
